# early L1 invalidate in grid barrier followers; 8-byte aligned MFMA runs in both GEMM K-loops
# speedup vs baseline: 1.0104x; 1.0104x over previous
.LBB0_411:
	s_add_i32 s84, s44, 2
	s_add_u32 s10, s42, 0x80
	s_addc_u32 s45, s43, 0
	s_add_i32 s52, 0, 0x10000
	s_cmp_eq_u32 s30, s44
	s_cselect_b32 s45, s81, s45
	s_cselect_b32 s44, s80, s10
	v_add_u32_e32 v32, s52, v216
	s_cselect_b32 s91, s83, s49
	s_cselect_b32 s90, s82, s48
	s_add_i32 s10, 0, 0x14000
	ds_read_b128 v[74:77], v32
	ds_read_b128 v[78:81], v32 offset:1024
	ds_read_b128 v[90:93], v32 offset:2048
	ds_read_b128 v[94:97], v32 offset:3072
	v_add_u32_e32 v32, s10, v216
	ds_read_b128 v[98:101], v32
	ds_read_b128 v[102:105], v32 offset:1024
	ds_read_b128 v[106:109], v32 offset:2048
	ds_read_b128 v[110:113], v32 offset:3072
	v_lshl_add_u64 v[188:189], s[42:43], 0, v[176:177]
	s_add_i32 m0, s3, 0xc000
	ds_read_b128 v[162:165], v218
	ds_read_b128 v[180:183], v218 offset:1024
	ds_read_b128 v[184:187], v218 offset:2048
	ds_read_b128 v[224:227], v218 offset:3072
	ds_read_b128 v[228:231], v218 offset:4096
	ds_read_b128 v[232:235], v218 offset:5120
	ds_read_b128 v[236:239], v218 offset:6144
	ds_read_b128 v[240:243], v218 offset:7168
	global_load_lds_dwordx4 v[188:189], off
	v_lshl_add_u64 v[188:189], s[42:43], 0, v[178:179]
	s_add_i32 m0, s3, 0xe000
	s_nop 0
	global_load_lds_dwordx4 v[188:189], off
	s_waitcnt vmcnt(8)
	s_waitcnt lgkmcnt(0)
	s_barrier
	s_setprio 1
	s_waitcnt lgkmcnt(0)
	s_nop 0
	v_mfma_f32_16x16x32_bf16 v[154:157], v[74:77], v[162:165], v[154:157]
	v_mfma_f32_16x16x32_bf16 v[158:161], v[90:93], v[162:165], v[158:161]
	v_mfma_f32_16x16x32_bf16 v[142:145], v[74:77], v[184:187], v[142:145]
	v_mfma_f32_16x16x32_bf16 v[138:141], v[90:93], v[184:187], v[138:141]
	v_mfma_f32_16x16x32_bf16 v[126:129], v[74:77], v[228:231], v[126:129]
	v_mfma_f32_16x16x32_bf16 v[122:125], v[90:93], v[228:231], v[122:125]
	v_mfma_f32_16x16x32_bf16 v[86:89], v[74:77], v[236:239], v[86:89]
	v_mfma_f32_16x16x32_bf16 v[82:85], v[90:93], v[236:239], v[82:85]
	v_mfma_f32_16x16x32_bf16 v[154:157], v[78:81], v[180:183], v[154:157]
	v_mfma_f32_16x16x32_bf16 v[158:161], v[94:97], v[180:183], v[158:161]
	v_mfma_f32_16x16x32_bf16 v[142:145], v[78:81], v[224:227], v[142:145]
	v_mfma_f32_16x16x32_bf16 v[138:141], v[94:97], v[224:227], v[138:141]
	v_mfma_f32_16x16x32_bf16 v[126:129], v[78:81], v[232:235], v[126:129]
	v_mfma_f32_16x16x32_bf16 v[122:125], v[94:97], v[232:235], v[122:125]
	v_mfma_f32_16x16x32_bf16 v[86:89], v[78:81], v[240:243], v[86:89]
	v_mfma_f32_16x16x32_bf16 v[82:85], v[94:97], v[240:243], v[82:85]
	s_setprio 0
	s_setprio 1
	v_mfma_f32_16x16x32_bf16 v[150:153], v[98:101], v[162:165], v[150:153]
	v_mfma_f32_16x16x32_bf16 v[146:149], v[106:109], v[162:165], v[146:149]
	v_mfma_f32_16x16x32_bf16 v[134:137], v[98:101], v[184:187], v[134:137]
	v_mfma_f32_16x16x32_bf16 v[130:133], v[106:109], v[184:187], v[130:133]
	v_mfma_f32_16x16x32_bf16 v[118:121], v[98:101], v[228:231], v[118:121]
	v_mfma_f32_16x16x32_bf16 v[114:117], v[106:109], v[228:231], v[114:117]
	v_mfma_f32_16x16x32_bf16 v[70:73], v[98:101], v[236:239], v[70:73]
	v_mfma_f32_16x16x32_bf16 v[66:69], v[106:109], v[236:239], v[66:69]
	v_mfma_f32_16x16x32_bf16 v[150:153], v[102:105], v[180:183], v[150:153]
	v_mfma_f32_16x16x32_bf16 v[146:149], v[110:113], v[180:183], v[146:149]
	v_mfma_f32_16x16x32_bf16 v[134:137], v[102:105], v[224:227], v[134:137]
	v_mfma_f32_16x16x32_bf16 v[130:133], v[110:113], v[224:227], v[130:133]
	v_mfma_f32_16x16x32_bf16 v[118:121], v[102:105], v[232:235], v[118:121]
	v_mfma_f32_16x16x32_bf16 v[114:117], v[110:113], v[232:235], v[114:117]
	v_mfma_f32_16x16x32_bf16 v[70:73], v[102:105], v[240:243], v[70:73]
	v_mfma_f32_16x16x32_bf16 v[66:69], v[110:113], v[240:243], v[66:69]
	s_setprio 0
	s_barrier
	s_add_i32 s52, s52, s2
	v_lshl_add_u64 v[188:189], s[90:91], 0, v[170:171]
	s_mov_b32 m0, s52
	s_bitcmp1_b32 s99, 0
	s_cbranch_scc1 .Lh_r0
	ds_read_b128 v[162:165], v218 offset:16384
	ds_read_b128 v[180:183], v218 offset:17408
	ds_read_b128 v[184:187], v218 offset:18432
	ds_read_b128 v[224:227], v218 offset:19456
	ds_read_b128 v[228:231], v218 offset:20480
	ds_read_b128 v[232:235], v218 offset:21504
	ds_read_b128 v[236:239], v218 offset:22528
	ds_read_b128 v[240:243], v218 offset:23552

.Lh_r2:
	global_load_lds_dwordx4 v[188:189], off
	v_lshl_add_u64 v[188:189], v[202:203], 0, s[56:57]
	s_add_i32 m0, s10, 0x2000
	s_add_i32 s10, s52, s2
	global_load_lds_dwordx4 v[188:189], off
	v_lshl_add_u64 v[188:189], v[204:205], 0, s[56:57]
	s_mov_b32 m0, s10
	s_nop 0
	global_load_lds_dwordx4 v[188:189], off
	v_lshl_add_u64 v[188:189], v[212:213], 0, s[56:57]
	s_add_i32 m0, s10, 0x2000
	s_nop 0
	global_load_lds_dwordx4 v[188:189], off
	v_lshl_add_u64 v[188:189], v[244:245], 0, s[56:57]
	s_mov_b32 m0, s13
	s_nop 0
	global_load_lds_dwordx4 v[188:189], off
	v_lshl_add_u64 v[188:189], v[246:247], 0, s[56:57]
	s_mov_b32 m0, s17
	s_nop 0
	global_load_lds_dwordx4 v[188:189], off
	s_waitcnt vmcnt(8)
	s_waitcnt lgkmcnt(0)
	s_barrier
	s_setprio 1
	s_waitcnt lgkmcnt(0)
	s_bitcmp1_b32 s99, 0
	s_cbranch_scc1 .Lh_m3
	s_nop 0
	v_mfma_f32_16x16x32_bf16 v[62:65], v[74:77], v[162:165], v[62:65]
	v_mfma_f32_16x16x32_bf16 v[58:61], v[90:93], v[162:165], v[58:61]
	v_mfma_f32_16x16x32_bf16 v[46:49], v[74:77], v[184:187], v[46:49]
	v_mfma_f32_16x16x32_bf16 v[42:45], v[90:93], v[184:187], v[42:45]
	v_mfma_f32_16x16x32_bf16 v[28:31], v[74:77], v[228:231], v[28:31]
	v_mfma_f32_16x16x32_bf16 v[24:27], v[90:93], v[228:231], v[24:27]
	v_mfma_f32_16x16x32_bf16 v[12:15], v[74:77], v[236:239], v[12:15]
	v_mfma_f32_16x16x32_bf16 v[8:11], v[90:93], v[236:239], v[8:11]
	v_mfma_f32_16x16x32_bf16 v[62:65], v[78:81], v[180:183], v[62:65]
	v_mfma_f32_16x16x32_bf16 v[58:61], v[94:97], v[180:183], v[58:61]
	v_mfma_f32_16x16x32_bf16 v[46:49], v[78:81], v[224:227], v[46:49]
	v_mfma_f32_16x16x32_bf16 v[42:45], v[94:97], v[224:227], v[42:45]
	v_mfma_f32_16x16x32_bf16 v[28:31], v[78:81], v[232:235], v[28:31]
	v_mfma_f32_16x16x32_bf16 v[24:27], v[94:97], v[232:235], v[24:27]
	v_mfma_f32_16x16x32_bf16 v[12:15], v[78:81], v[240:243], v[12:15]
	v_mfma_f32_16x16x32_bf16 v[8:11], v[94:97], v[240:243], v[8:11]
	s_setprio 0
	s_setprio 1
	v_mfma_f32_16x16x32_bf16 v[54:57], v[98:101], v[162:165], v[54:57]
	v_mfma_f32_16x16x32_bf16 v[50:53], v[106:109], v[162:165], v[50:53]
	v_mfma_f32_16x16x32_bf16 v[38:41], v[98:101], v[184:187], v[38:41]
	v_mfma_f32_16x16x32_bf16 v[34:37], v[106:109], v[184:187], v[34:37]
	v_mfma_f32_16x16x32_bf16 v[20:23], v[98:101], v[228:231], v[20:23]
	v_mfma_f32_16x16x32_bf16 v[16:19], v[106:109], v[228:231], v[16:19]
	v_mfma_f32_16x16x32_bf16 v[4:7], v[98:101], v[236:239], v[4:7]
	v_mfma_f32_16x16x32_bf16 v[0:3], v[106:109], v[236:239], v[0:3]
	v_mfma_f32_16x16x32_bf16 v[54:57], v[102:105], v[180:183], v[54:57]
	v_mfma_f32_16x16x32_bf16 v[50:53], v[110:113], v[180:183], v[50:53]
	v_mfma_f32_16x16x32_bf16 v[38:41], v[102:105], v[224:227], v[38:41]
	v_mfma_f32_16x16x32_bf16 v[34:37], v[110:113], v[224:227], v[34:37]
	v_mfma_f32_16x16x32_bf16 v[20:23], v[102:105], v[232:235], v[20:23]
	v_mfma_f32_16x16x32_bf16 v[16:19], v[110:113], v[232:235], v[16:19]
	v_mfma_f32_16x16x32_bf16 v[4:7], v[102:105], v[240:243], v[4:7]
	v_mfma_f32_16x16x32_bf16 v[0:3], v[110:113], v[240:243], v[0:3]

.LBB0_559:
	s_add_i32 s49, s42, 2
	s_add_u32 vcc_lo, s0, 0x80
	s_addc_u32 s43, s1, 0
	s_add_i32 s10, 0, 0x10000
	s_cmp_eq_u32 s47, s42
	s_cselect_b32 s43, s35, s43
	s_cselect_b32 s42, s34, vcc_lo
	s_cselect_b32 vcc_hi, s29, s45
	s_cselect_b32 vcc_lo, s28, s44
	s_add_i32 s52, 0, 0x14000
	v_add_u32_e32 v86, s10, v172
	v_add_u32_e32 v175, s52, v172
	ds_read_b128 v[66:69], v86
	ds_read_b128 v[70:73], v86 offset:1024
	ds_read_b128 v[82:85], v86 offset:2048
	ds_read_b128 v[86:89], v86 offset:3072
	ds_read_b128 v[146:149], v175
	ds_read_b128 v[162:165], v175 offset:1024
	ds_read_b128 v[168:171], v175 offset:2048
	ds_read_b128 v[176:179], v175 offset:3072
	v_lshl_add_u64 v[188:189], s[0:1], 0, v[158:159]
	s_add_i32 m0, s7, 0xc000
	ds_read_b128 v[180:183], v174
	ds_read_b128 v[184:187], v174 offset:1024
	ds_read_b128 v[216:219], v174 offset:2048
	ds_read_b128 v[224:227], v174 offset:3072
	ds_read_b128 v[228:231], v174 offset:4096
	ds_read_b128 v[232:235], v174 offset:5120
	ds_read_b128 v[236:239], v174 offset:6144
	ds_read_b128 v[240:243], v174 offset:7168
	global_load_lds_dwordx4 v[188:189], off
	v_lshl_add_u64 v[188:189], s[0:1], 0, v[160:161]
	s_add_i32 m0, s7, 0xe000
	s_nop 0
	global_load_lds_dwordx4 v[188:189], off
	s_waitcnt vmcnt(8)
	s_waitcnt lgkmcnt(0)
	s_barrier
	s_setprio 1
	s_waitcnt lgkmcnt(0)
	v_mfma_f32_16x16x32_bf16 v[138:141], v[66:69], v[180:183], v[138:141]
	v_mfma_f32_16x16x32_bf16 v[142:145], v[82:85], v[180:183], v[142:145]
	v_mfma_f32_16x16x32_bf16 v[126:129], v[66:69], v[216:219], v[126:129]
	v_mfma_f32_16x16x32_bf16 v[122:125], v[82:85], v[216:219], v[122:125]
	v_mfma_f32_16x16x32_bf16 v[110:113], v[66:69], v[228:231], v[110:113]
	v_mfma_f32_16x16x32_bf16 v[106:109], v[82:85], v[228:231], v[106:109]
	v_mfma_f32_16x16x32_bf16 v[94:97], v[66:69], v[236:239], v[94:97]
	v_mfma_f32_16x16x32_bf16 v[90:93], v[82:85], v[236:239], v[90:93]
	v_mfma_f32_16x16x32_bf16 v[138:141], v[70:73], v[184:187], v[138:141]
	v_mfma_f32_16x16x32_bf16 v[142:145], v[86:89], v[184:187], v[142:145]
	v_mfma_f32_16x16x32_bf16 v[126:129], v[70:73], v[224:227], v[126:129]
	v_mfma_f32_16x16x32_bf16 v[122:125], v[86:89], v[224:227], v[122:125]
	v_mfma_f32_16x16x32_bf16 v[110:113], v[70:73], v[232:235], v[110:113]
	v_mfma_f32_16x16x32_bf16 v[106:109], v[86:89], v[232:235], v[106:109]
	v_mfma_f32_16x16x32_bf16 v[94:97], v[70:73], v[240:243], v[94:97]
	v_mfma_f32_16x16x32_bf16 v[90:93], v[86:89], v[240:243], v[90:93]
	s_setprio 0
	s_setprio 1
	v_mfma_f32_16x16x32_bf16 v[134:137], v[146:149], v[180:183], v[134:137]
	v_mfma_f32_16x16x32_bf16 v[130:133], v[168:171], v[180:183], v[130:133]
	v_mfma_f32_16x16x32_bf16 v[118:121], v[146:149], v[216:219], v[118:121]
	v_mfma_f32_16x16x32_bf16 v[114:117], v[168:171], v[216:219], v[114:117]
	v_mfma_f32_16x16x32_bf16 v[102:105], v[146:149], v[228:231], v[102:105]
	v_mfma_f32_16x16x32_bf16 v[98:101], v[168:171], v[228:231], v[98:101]
	v_mfma_f32_16x16x32_bf16 v[78:81], v[146:149], v[236:239], v[78:81]
	v_mfma_f32_16x16x32_bf16 v[74:77], v[168:171], v[236:239], v[74:77]
	v_mfma_f32_16x16x32_bf16 v[134:137], v[162:165], v[184:187], v[134:137]
	v_mfma_f32_16x16x32_bf16 v[130:133], v[176:179], v[184:187], v[130:133]
	v_mfma_f32_16x16x32_bf16 v[118:121], v[162:165], v[224:227], v[118:121]
	v_mfma_f32_16x16x32_bf16 v[114:117], v[176:179], v[224:227], v[114:117]
	v_mfma_f32_16x16x32_bf16 v[102:105], v[162:165], v[232:235], v[102:105]
	v_mfma_f32_16x16x32_bf16 v[98:101], v[176:179], v[232:235], v[98:101]
	v_mfma_f32_16x16x32_bf16 v[78:81], v[162:165], v[240:243], v[78:81]
	v_mfma_f32_16x16x32_bf16 v[74:77], v[176:179], v[240:243], v[74:77]
	s_setprio 0
	s_barrier
	s_add_i32 s10, s10, s94
	v_lshl_add_u64 v[188:189], vcc, 0, v[32:33]
	s_mov_b32 m0, s10
	ds_read_b128 v[180:183], v174 offset:16384
	ds_read_b128 v[184:187], v174 offset:17408
	ds_read_b128 v[216:219], v174 offset:18432
	ds_read_b128 v[224:227], v174 offset:19456
	ds_read_b128 v[228:231], v174 offset:20480
	ds_read_b128 v[232:235], v174 offset:21504
	ds_read_b128 v[236:239], v174 offset:22528
	ds_read_b128 v[240:243], v174 offset:23552
	global_load_lds_dwordx4 v[188:189], off
	s_add_i32 m0, s10, 0x2000
	v_lshl_add_u64 v[244:245], vcc, 0, v[154:155]
	s_add_u32 vcc_lo, vcc_lo, s96
	s_addc_u32 vcc_hi, vcc_hi, s97
	s_add_i32 s10, s52, s94
	global_load_lds_dwordx4 v[244:245], off
	v_lshl_add_u64 v[246:247], vcc, 0, v[32:33]
	s_mov_b32 m0, s10
	v_lshl_add_u64 v[248:249], vcc, 0, v[154:155]
	global_load_lds_dwordx4 v[246:247], off
	s_add_i32 m0, s10, 0x2000
	v_lshl_add_u64 v[202:203], s[42:43], 0, v[150:151]
	global_load_lds_dwordx4 v[248:249], off
	s_mov_b32 m0, s7
	v_lshl_add_u64 v[212:213], s[42:43], 0, v[152:153]
	global_load_lds_dwordx4 v[202:203], off
	s_mov_b32 m0, s2
	s_nop 0
	global_load_lds_dwordx4 v[212:213], off
	s_waitcnt vmcnt(8)
	s_waitcnt lgkmcnt(0)
	s_barrier
	s_setprio 1
	s_waitcnt lgkmcnt(0)
	v_mfma_f32_16x16x32_bf16 v[62:65], v[66:69], v[180:183], v[62:65]
	v_mfma_f32_16x16x32_bf16 v[58:61], v[82:85], v[180:183], v[58:61]
	v_mfma_f32_16x16x32_bf16 v[46:49], v[66:69], v[216:219], v[46:49]
	v_mfma_f32_16x16x32_bf16 v[42:45], v[82:85], v[216:219], v[42:45]
	v_mfma_f32_16x16x32_bf16 v[28:31], v[66:69], v[228:231], v[28:31]
	v_mfma_f32_16x16x32_bf16 v[24:27], v[82:85], v[228:231], v[24:27]
	v_mfma_f32_16x16x32_bf16 v[12:15], v[66:69], v[236:239], v[12:15]
	v_mfma_f32_16x16x32_bf16 v[8:11], v[82:85], v[236:239], v[8:11]
	v_mfma_f32_16x16x32_bf16 v[62:65], v[70:73], v[184:187], v[62:65]
	v_mfma_f32_16x16x32_bf16 v[58:61], v[86:89], v[184:187], v[58:61]
	v_mfma_f32_16x16x32_bf16 v[46:49], v[70:73], v[224:227], v[46:49]
	v_mfma_f32_16x16x32_bf16 v[42:45], v[86:89], v[224:227], v[42:45]
	v_mfma_f32_16x16x32_bf16 v[28:31], v[70:73], v[232:235], v[28:31]
	v_mfma_f32_16x16x32_bf16 v[24:27], v[86:89], v[232:235], v[24:27]
	v_mfma_f32_16x16x32_bf16 v[12:15], v[70:73], v[240:243], v[12:15]
	v_mfma_f32_16x16x32_bf16 v[8:11], v[86:89], v[240:243], v[8:11]
	s_setprio 0
	s_setprio 1
	v_mfma_f32_16x16x32_bf16 v[54:57], v[146:149], v[180:183], v[54:57]
	v_mfma_f32_16x16x32_bf16 v[50:53], v[168:171], v[180:183], v[50:53]
	v_mfma_f32_16x16x32_bf16 v[38:41], v[146:149], v[216:219], v[38:41]
	v_mfma_f32_16x16x32_bf16 v[34:37], v[168:171], v[216:219], v[34:37]
	v_mfma_f32_16x16x32_bf16 v[20:23], v[146:149], v[228:231], v[20:23]
	v_mfma_f32_16x16x32_bf16 v[16:19], v[168:171], v[228:231], v[16:19]
	v_mfma_f32_16x16x32_bf16 v[4:7], v[146:149], v[236:239], v[4:7]
	v_mfma_f32_16x16x32_bf16 v[0:3], v[168:171], v[236:239], v[0:3]
	v_mfma_f32_16x16x32_bf16 v[54:57], v[162:165], v[184:187], v[54:57]
	v_mfma_f32_16x16x32_bf16 v[50:53], v[176:179], v[184:187], v[50:53]
	v_mfma_f32_16x16x32_bf16 v[38:41], v[162:165], v[224:227], v[38:41]
	v_mfma_f32_16x16x32_bf16 v[34:37], v[176:179], v[224:227], v[34:37]
	v_mfma_f32_16x16x32_bf16 v[20:23], v[162:165], v[232:235], v[20:23]
	v_mfma_f32_16x16x32_bf16 v[16:19], v[176:179], v[232:235], v[16:19]
	v_mfma_f32_16x16x32_bf16 v[4:7], v[162:165], v[240:243], v[4:7]
	v_mfma_f32_16x16x32_bf16 v[0:3], v[176:179], v[240:243], v[0:3]
	s_setprio 0
	s_barrier
	s_add_i32 s10, 0, 0x18000
	s_add_i32 s52, 0, 0x1c000
	v_add_u32_e32 v86, s10, v172
	v_add_u32_e32 v175, s52, v172
	ds_read_b128 v[66:69], v86
	ds_read_b128 v[70:73], v86 offset:1024
	ds_read_b128 v[82:85], v86 offset:2048
	ds_read_b128 v[86:89], v86 offset:3072
	ds_read_b128 v[146:149], v175
	ds_read_b128 v[162:165], v175 offset:1024
	ds_read_b128 v[168:171], v175 offset:2048
	ds_read_b128 v[176:179], v175 offset:3072
	s_add_u32 s42, s42, s96
	s_addc_u32 s43, s43, s97
	s_mov_b32 m0, s3
	v_lshl_add_u64 v[204:205], s[42:43], 0, v[150:151]
	ds_read_b128 v[180:183], v174 offset:32768
	ds_read_b128 v[184:187], v174 offset:33792
	ds_read_b128 v[216:219], v174 offset:34816
	ds_read_b128 v[224:227], v174 offset:35840
	ds_read_b128 v[228:231], v174 offset:36864
	ds_read_b128 v[232:235], v174 offset:37888
	ds_read_b128 v[236:239], v174 offset:38912
	ds_read_b128 v[240:243], v174 offset:39936
	global_load_lds_dwordx4 v[204:205], off
	v_lshl_add_u64 v[204:205], s[42:43], 0, v[152:153]
	s_mov_b32 m0, s17
	s_nop 0
	global_load_lds_dwordx4 v[204:205], off
	s_waitcnt vmcnt(8)
	s_waitcnt lgkmcnt(0)
	s_barrier
	s_setprio 1
	s_waitcnt lgkmcnt(0)
	v_mfma_f32_16x16x32_bf16 v[138:141], v[66:69], v[180:183], v[138:141]
	v_mfma_f32_16x16x32_bf16 v[142:145], v[82:85], v[180:183], v[142:145]
	v_mfma_f32_16x16x32_bf16 v[126:129], v[66:69], v[216:219], v[126:129]
	v_mfma_f32_16x16x32_bf16 v[122:125], v[82:85], v[216:219], v[122:125]
	v_mfma_f32_16x16x32_bf16 v[110:113], v[66:69], v[228:231], v[110:113]
	v_mfma_f32_16x16x32_bf16 v[106:109], v[82:85], v[228:231], v[106:109]
	v_mfma_f32_16x16x32_bf16 v[94:97], v[66:69], v[236:239], v[94:97]
	v_mfma_f32_16x16x32_bf16 v[90:93], v[82:85], v[236:239], v[90:93]
	v_mfma_f32_16x16x32_bf16 v[138:141], v[70:73], v[184:187], v[138:141]
	v_mfma_f32_16x16x32_bf16 v[142:145], v[86:89], v[184:187], v[142:145]
	v_mfma_f32_16x16x32_bf16 v[126:129], v[70:73], v[224:227], v[126:129]
	v_mfma_f32_16x16x32_bf16 v[122:125], v[86:89], v[224:227], v[122:125]
	v_mfma_f32_16x16x32_bf16 v[110:113], v[70:73], v[232:235], v[110:113]
	v_mfma_f32_16x16x32_bf16 v[106:109], v[86:89], v[232:235], v[106:109]
	v_mfma_f32_16x16x32_bf16 v[94:97], v[70:73], v[240:243], v[94:97]
	v_mfma_f32_16x16x32_bf16 v[90:93], v[86:89], v[240:243], v[90:93]
	s_setprio 0
	s_setprio 1
	v_mfma_f32_16x16x32_bf16 v[134:137], v[146:149], v[180:183], v[134:137]
	v_mfma_f32_16x16x32_bf16 v[130:133], v[168:171], v[180:183], v[130:133]
	v_mfma_f32_16x16x32_bf16 v[118:121], v[146:149], v[216:219], v[118:121]
	v_mfma_f32_16x16x32_bf16 v[114:117], v[168:171], v[216:219], v[114:117]
	v_mfma_f32_16x16x32_bf16 v[102:105], v[146:149], v[228:231], v[102:105]
	v_mfma_f32_16x16x32_bf16 v[98:101], v[168:171], v[228:231], v[98:101]
	v_mfma_f32_16x16x32_bf16 v[78:81], v[146:149], v[236:239], v[78:81]
	v_mfma_f32_16x16x32_bf16 v[74:77], v[168:171], v[236:239], v[74:77]
	v_mfma_f32_16x16x32_bf16 v[134:137], v[162:165], v[184:187], v[134:137]
	v_mfma_f32_16x16x32_bf16 v[130:133], v[176:179], v[184:187], v[130:133]
	v_mfma_f32_16x16x32_bf16 v[118:121], v[162:165], v[224:227], v[118:121]
	v_mfma_f32_16x16x32_bf16 v[114:117], v[176:179], v[224:227], v[114:117]
	v_mfma_f32_16x16x32_bf16 v[102:105], v[162:165], v[232:235], v[102:105]
	v_mfma_f32_16x16x32_bf16 v[98:101], v[176:179], v[232:235], v[98:101]
	v_mfma_f32_16x16x32_bf16 v[78:81], v[162:165], v[240:243], v[78:81]
	v_mfma_f32_16x16x32_bf16 v[74:77], v[176:179], v[240:243], v[74:77]
	s_setprio 0
	s_barrier
	s_add_i32 s10, s10, s94
	v_lshl_add_u64 v[188:189], v[188:189], 0, s[56:57]
	s_mov_b32 m0, s10
	ds_read_b128 v[180:183], v174 offset:49152
	ds_read_b128 v[184:187], v174 offset:50176
	ds_read_b128 v[216:219], v174 offset:51200
	ds_read_b128 v[224:227], v174 offset:52224
	ds_read_b128 v[228:231], v174 offset:53248
	ds_read_b128 v[232:235], v174 offset:54272
	ds_read_b128 v[236:239], v174 offset:55296
	ds_read_b128 v[240:243], v174 offset:56320
	global_load_lds_dwordx4 v[188:189], off
	v_lshl_add_u64 v[188:189], v[244:245], 0, s[56:57]
	s_add_i32 m0, s10, 0x2000
	s_add_i32 s10, s52, s94
	global_load_lds_dwordx4 v[188:189], off
	v_lshl_add_u64 v[188:189], v[246:247], 0, s[56:57]
	s_mov_b32 m0, s10
	s_nop 0
	global_load_lds_dwordx4 v[188:189], off
	v_lshl_add_u64 v[188:189], v[248:249], 0, s[56:57]
	s_add_i32 m0, s10, 0x2000
	s_nop 0
	global_load_lds_dwordx4 v[188:189], off
	v_lshl_add_u64 v[188:189], v[202:203], 0, s[56:57]
	s_mov_b32 m0, s13
	s_nop 0
	global_load_lds_dwordx4 v[188:189], off
	v_lshl_add_u64 v[188:189], v[212:213], 0, s[56:57]
	s_mov_b32 m0, s46
	s_nop 0
	global_load_lds_dwordx4 v[188:189], off
	s_waitcnt vmcnt(8)
	s_waitcnt lgkmcnt(0)
	s_barrier
	s_setprio 1
	s_waitcnt lgkmcnt(0)
	s_nop 0
	v_mfma_f32_16x16x32_bf16 v[62:65], v[66:69], v[180:183], v[62:65]
	v_mfma_f32_16x16x32_bf16 v[58:61], v[82:85], v[180:183], v[58:61]
	v_mfma_f32_16x16x32_bf16 v[46:49], v[66:69], v[216:219], v[46:49]
	v_mfma_f32_16x16x32_bf16 v[42:45], v[82:85], v[216:219], v[42:45]
	v_mfma_f32_16x16x32_bf16 v[28:31], v[66:69], v[228:231], v[28:31]
	v_mfma_f32_16x16x32_bf16 v[24:27], v[82:85], v[228:231], v[24:27]
	v_mfma_f32_16x16x32_bf16 v[12:15], v[66:69], v[236:239], v[12:15]
	v_mfma_f32_16x16x32_bf16 v[8:11], v[82:85], v[236:239], v[8:11]
	v_mfma_f32_16x16x32_bf16 v[62:65], v[70:73], v[184:187], v[62:65]
	v_mfma_f32_16x16x32_bf16 v[58:61], v[86:89], v[184:187], v[58:61]
	v_mfma_f32_16x16x32_bf16 v[46:49], v[70:73], v[224:227], v[46:49]
	v_mfma_f32_16x16x32_bf16 v[42:45], v[86:89], v[224:227], v[42:45]
	v_mfma_f32_16x16x32_bf16 v[28:31], v[70:73], v[232:235], v[28:31]
	v_mfma_f32_16x16x32_bf16 v[24:27], v[86:89], v[232:235], v[24:27]
	v_mfma_f32_16x16x32_bf16 v[12:15], v[70:73], v[240:243], v[12:15]
	v_mfma_f32_16x16x32_bf16 v[8:11], v[86:89], v[240:243], v[8:11]
	s_setprio 0
	s_setprio 1
	v_mfma_f32_16x16x32_bf16 v[54:57], v[146:149], v[180:183], v[54:57]
	v_mfma_f32_16x16x32_bf16 v[50:53], v[168:171], v[180:183], v[50:53]
	v_mfma_f32_16x16x32_bf16 v[38:41], v[146:149], v[216:219], v[38:41]
	v_mfma_f32_16x16x32_bf16 v[34:37], v[168:171], v[216:219], v[34:37]
	v_mfma_f32_16x16x32_bf16 v[20:23], v[146:149], v[228:231], v[20:23]
	v_mfma_f32_16x16x32_bf16 v[16:19], v[168:171], v[228:231], v[16:19]
	v_mfma_f32_16x16x32_bf16 v[4:7], v[146:149], v[236:239], v[4:7]
	v_mfma_f32_16x16x32_bf16 v[0:3], v[168:171], v[236:239], v[0:3]
	v_mfma_f32_16x16x32_bf16 v[54:57], v[162:165], v[184:187], v[54:57]
	v_mfma_f32_16x16x32_bf16 v[50:53], v[176:179], v[184:187], v[50:53]
	v_mfma_f32_16x16x32_bf16 v[38:41], v[162:165], v[224:227], v[38:41]
	v_mfma_f32_16x16x32_bf16 v[34:37], v[176:179], v[224:227], v[34:37]
	v_mfma_f32_16x16x32_bf16 v[20:23], v[162:165], v[232:235], v[20:23]
	v_mfma_f32_16x16x32_bf16 v[16:19], v[176:179], v[232:235], v[16:19]
	v_mfma_f32_16x16x32_bf16 v[4:7], v[162:165], v[240:243], v[4:7]
	v_mfma_f32_16x16x32_bf16 v[0:3], v[176:179], v[240:243], v[0:3]
	s_setprio 0
	s_barrier
	s_add_u32 s0, s0, 0x100
	s_addc_u32 s1, s1, 0
	s_add_u32 s44, s44, 0x100
	s_addc_u32 s45, s45, 0
	s_cmp_ge_i32 s49, s20
	s_mov_b32 s42, s49
	s_cbranch_scc0 .LBB0_559
	v_readlane_b32 s52, v252, 10
	v_readlane_b32 s53, v252, 11

.LBB0_797:
	s_or_b64 exec, exec, s[2:3]
	v_cvt_f32_u32_e32 v2, v195
	s_waitcnt vmcnt(0)
	v_readfirstlane_b32 s2, v1
	v_sub_u32_e32 v1, 0, v195
	v_rcp_iflag_f32_e32 v2, v2
	v_add_u32_e32 v3, s2, v0
	v_mul_f32_e32 v2, 0x4f7ffffe, v2
	v_cvt_u32_f32_e32 v2, v2
	v_mul_lo_u32 v0, v1, v2
	v_mul_hi_u32 v0, v2, v0
	v_add_u32_e32 v0, v2, v0
	v_mul_hi_u32 v0, v3, v0
	v_mul_lo_u32 v1, v0, v195
	v_sub_u32_e32 v1, v3, v1
	v_add_u32_e32 v2, 1, v0
	v_cmp_ge_u32_e32 vcc, v1, v195
	s_nop 1
	v_cndmask_b32_e32 v0, v0, v2, vcc
	v_sub_u32_e32 v2, v1, v195
	v_cndmask_b32_e32 v1, v1, v2, vcc
	v_add_u32_e32 v2, 1, v0
	v_cmp_ge_u32_e32 vcc, v1, v195
	v_add_u32_e32 v1, 1, v3
	s_nop 0
	v_cndmask_b32_e32 v0, v0, v2, vcc
	v_mul_lo_u32 v2, v195, v0
	v_add_u32_e32 v2, v2, v195
	v_cmp_ne_u32_e32 vcc, v1, v2
	s_and_saveexec_b64 s[2:3], vcc
	s_xor_b64 s[2:3], exec, s[2:3]
	s_cbranch_execz .LBB0_939
	buffer_inv sc1
	s_mov_b32 s6, 0x1000000
	s_mov_b64 s[24:25], 0
	s_branch .LBB0_927

.LBB0_937:
	s_mov_b64 s[34:35], -1
	s_branch .LBB0_925
.LBB0_938:
	s_or_b64 exec, exec, s[24:25]
	s_waitcnt vmcnt(0)
.LBB0_939:
	s_andn2_saveexec_b64 s[2:3], s[2:3]
	s_cbranch_execz .LBB0_972
	s_mov_b64 s[2:3], exec
	buffer_wbl2 sc1
	s_waitcnt vmcnt(0)
	v_mbcnt_lo_u32_b32 v0, s2, 0
	v_mbcnt_hi_u32_b32 v0, s3, v0
	v_cmp_eq_u32_e32 vcc, 0, v0
	s_and_saveexec_b64 s[24:25], vcc
	s_cbranch_execz .LBB0_942
	s_bcnt1_i32_b64 s2, s[2:3]
	v_mov_b32_e32 v1, s2
	v_readlane_b32 s2, v253, 52
	v_readlane_b32 s3, v253, 53
	s_nop 4
	global_atomic_add v1, v33, v1, s[2:3] sc0
